# SwiGLU GEMM tile head waits only for the next tile's first K-slice (epilogue stores stay in flight)
# baseline (speedup 1.0000x reference)
.LBB0_919:
	v_mul_f32_e32 v132, 0xbfb8aa3b, v122
	v_exp_f32_e32 v132, v132
	v_mbcnt_lo_u32_b32 v0, -1, 0
	v_mbcnt_hi_u32_b32 v0, -1, v0
	v_lshl_add_u32 v0, s69, 6, v0
	s_ashr_i32 s2, s24, 1
	v_lshrrev_b32_e32 v130, 1, v0
	v_add_f32_e32 v132, 1.0, v132
	v_rcp_f32_e32 v132, v132
	v_and_b32_e32 v130, 0x78, v130
	v_or_b32_e32 v130, s2, v130
	v_ashrrev_i32_e32 v131, 2, v0
	v_mul_f32_e32 v122, v122, v132
	v_mul_f32_e32 v122, v122, v126
	v_mul_f32_e32 v126, 0xbfb8aa3b, v123
	v_exp_f32_e32 v126, v126
	v_readlane_b32 s2, v255, 18
	v_and_b32_e32 v131, 0xffffffc0, v131
	v_and_or_b32 v0, v0, 15, s22
	v_add_f32_e32 v126, 1.0, v126
	v_rcp_f32_e32 v126, v126
	v_readlane_b32 s3, v255, 19
	v_add_u32_e32 v0, v0, v131
	v_ashrrev_i32_e32 v131, 31, v130
	v_mul_f32_e32 v123, v123, v126
	v_mul_f32_e32 v126, 0xbfb8aa3b, v124
	v_exp_f32_e32 v126, v126
	v_mul_f32_e32 v123, v123, v127
	s_movk_i32 s10, 0x1600
	s_and_b64 vcc, exec, s[16:17]
	v_add_f32_e32 v126, 1.0, v126
	v_rcp_f32_e32 v126, v126
	s_mov_b32 s22, s20
	s_mov_b32 s24, s18
	v_mul_f32_e32 v124, v124, v126
	v_mul_f32_e32 v126, 0xbfb8aa3b, v125
	v_exp_f32_e32 v126, v126
	v_mul_f32_e32 v124, v124, v128
	v_add_f32_e32 v126, 1.0, v126
	v_rcp_f32_e32 v126, v126
	s_nop 0
	v_mul_f32_e32 v125, v125, v126
	v_mul_f32_e32 v126, 0xbfb8aa3b, v114
	v_exp_f32_e32 v126, v126
	v_mul_f32_e32 v125, v125, v129
	v_add_f32_e32 v126, 1.0, v126
	v_rcp_f32_e32 v126, v126
	s_nop 0
	v_mul_f32_e32 v114, v114, v126
	v_mul_f32_e32 v114, v114, v118
	v_mul_f32_e32 v118, 0xbfb8aa3b, v115
	v_exp_f32_e32 v118, v118
	s_nop 0
	v_add_f32_e32 v118, 1.0, v118
	v_rcp_f32_e32 v118, v118
	s_nop 0
	v_mul_f32_e32 v115, v115, v118
	v_mul_f32_e32 v118, 0xbfb8aa3b, v116
	v_exp_f32_e32 v118, v118
	v_mul_f32_e32 v115, v115, v119
	v_cvt_pk_bf16_f32 v119, v124, v125
	v_add_f32_e32 v118, 1.0, v118
	v_rcp_f32_e32 v118, v118
	s_nop 0
	v_mul_f32_e32 v116, v116, v118
	v_mul_f32_e32 v118, 0xbfb8aa3b, v117
	v_exp_f32_e32 v118, v118
	v_mul_f32_e32 v116, v116, v120
	v_cvt_pk_bf16_f32 v120, v114, v115
	v_mov_b64_e32 v[114:115], s[2:3]
	v_add_f32_e32 v118, 1.0, v118
	v_rcp_f32_e32 v118, v118
	s_nop 0
	v_mul_f32_e32 v117, v117, v118
	v_mul_f32_e32 v117, v117, v121
	v_cvt_pk_bf16_f32 v118, v122, v123
	v_cvt_pk_bf16_f32 v121, v116, v117
	v_mad_i64_i32 v[122:123], s[2:3], v0, s10, v[114:115]
	v_lshlrev_b64 v[116:117], 1, v[130:131]
	v_lshl_add_u64 v[122:123], v[122:123], 0, v[116:117]
	global_store_dwordx4 v[122:123], v[118:121], off
	s_nop 1
	v_mul_f32_e32 v119, 0xbfb8aa3b, v106
	v_exp_f32_e32 v119, v119
	v_or_b32_e32 v118, 16, v0
	v_add_f32_e32 v119, 1.0, v119
	v_rcp_f32_e32 v119, v119
	s_nop 0
	v_mul_f32_e32 v106, v106, v119
	v_mul_f32_e32 v106, v106, v110
	v_mul_f32_e32 v110, 0xbfb8aa3b, v107
	v_exp_f32_e32 v110, v110
	s_nop 0
	v_add_f32_e32 v110, 1.0, v110
	v_rcp_f32_e32 v110, v110
	s_nop 0
	v_mul_f32_e32 v107, v107, v110
	v_mul_f32_e32 v110, 0xbfb8aa3b, v108
	v_exp_f32_e32 v110, v110
	v_mul_f32_e32 v107, v107, v111
	v_add_f32_e32 v110, 1.0, v110
	v_rcp_f32_e32 v110, v110
	s_nop 0
	v_mul_f32_e32 v108, v108, v110
	v_mul_f32_e32 v110, 0xbfb8aa3b, v109
	v_exp_f32_e32 v110, v110
	v_mul_f32_e32 v108, v108, v112
	v_add_f32_e32 v110, 1.0, v110
	v_rcp_f32_e32 v110, v110
	s_nop 0
	v_mul_f32_e32 v109, v109, v110
	v_mul_f32_e32 v110, 0xbfb8aa3b, v98
	v_exp_f32_e32 v110, v110
	v_mul_f32_e32 v109, v109, v113
	v_add_f32_e32 v110, 1.0, v110
	v_rcp_f32_e32 v110, v110
	s_nop 0
	v_mul_f32_e32 v98, v98, v110
	v_mul_f32_e32 v102, v98, v102
	v_mul_f32_e32 v98, 0xbfb8aa3b, v99
	v_exp_f32_e32 v98, v98
	s_nop 0
	v_add_f32_e32 v98, 1.0, v98
	v_rcp_f32_e32 v98, v98
	s_nop 0
	v_mul_f32_e32 v98, v99, v98
	v_mul_f32_e32 v103, v98, v103
	v_mul_f32_e32 v98, 0xbfb8aa3b, v100
	v_exp_f32_e32 v98, v98
	v_cvt_pk_bf16_f32 v99, v108, v109
	s_nop 0
	v_add_f32_e32 v98, 1.0, v98
	v_rcp_f32_e32 v98, v98
	s_nop 0
	v_mul_f32_e32 v98, v100, v98
	v_mul_f32_e32 v104, v98, v104
	v_mul_f32_e32 v98, 0xbfb8aa3b, v101
	v_exp_f32_e32 v98, v98
	v_cvt_pk_bf16_f32 v100, v102, v103
	v_mad_i64_i32 v[102:103], s[2:3], v118, s10, v[114:115]
	v_add_f32_e32 v98, 1.0, v98
	v_rcp_f32_e32 v98, v98
	v_lshl_add_u64 v[102:103], v[102:103], 0, v[116:117]
	v_mul_f32_e32 v98, v101, v98
	v_mul_f32_e32 v101, v98, v105
	v_cvt_pk_bf16_f32 v98, v106, v107
	v_cvt_pk_bf16_f32 v101, v104, v101
	global_store_dwordx4 v[102:103], v[98:101], off
	s_nop 1
	v_mul_f32_e32 v99, 0xbfb8aa3b, v90
	v_exp_f32_e32 v99, v99
	v_or_b32_e32 v98, 32, v0
	v_add_f32_e32 v99, 1.0, v99
	v_rcp_f32_e32 v99, v99
	s_nop 0
	v_mul_f32_e32 v90, v90, v99
	v_mul_f32_e32 v90, v90, v94
	v_mul_f32_e32 v94, 0xbfb8aa3b, v91
	v_exp_f32_e32 v94, v94
	s_nop 0
	v_add_f32_e32 v94, 1.0, v94
	v_rcp_f32_e32 v94, v94
	s_nop 0
	v_mul_f32_e32 v91, v91, v94
	v_mul_f32_e32 v94, 0xbfb8aa3b, v92
	v_exp_f32_e32 v94, v94
	v_mul_f32_e32 v91, v91, v95
	v_add_f32_e32 v94, 1.0, v94
	v_rcp_f32_e32 v94, v94
	s_nop 0
	v_mul_f32_e32 v92, v92, v94
	v_mul_f32_e32 v94, 0xbfb8aa3b, v93
	v_exp_f32_e32 v94, v94
	v_mul_f32_e32 v92, v92, v96
	v_add_f32_e32 v94, 1.0, v94
	v_rcp_f32_e32 v94, v94
	s_nop 0
	v_mul_f32_e32 v93, v93, v94
	v_mul_f32_e32 v94, 0xbfb8aa3b, v82
	v_exp_f32_e32 v94, v94
	v_mul_f32_e32 v93, v93, v97
	v_add_f32_e32 v94, 1.0, v94
	v_rcp_f32_e32 v94, v94
	s_nop 0
	v_mul_f32_e32 v82, v82, v94
	v_mul_f32_e32 v86, v82, v86
	v_mul_f32_e32 v82, 0xbfb8aa3b, v83
	v_exp_f32_e32 v82, v82
	s_nop 0
	v_add_f32_e32 v82, 1.0, v82
	v_rcp_f32_e32 v82, v82
	s_nop 0
	v_mul_f32_e32 v82, v83, v82
	v_mul_f32_e32 v87, v82, v87
	v_mul_f32_e32 v82, 0xbfb8aa3b, v84
	v_exp_f32_e32 v82, v82
	v_cvt_pk_bf16_f32 v83, v92, v93
	s_nop 0
	v_add_f32_e32 v82, 1.0, v82
	v_rcp_f32_e32 v82, v82
	s_nop 0
	v_mul_f32_e32 v82, v84, v82
	v_mul_f32_e32 v88, v82, v88
	v_mul_f32_e32 v82, 0xbfb8aa3b, v85
	v_exp_f32_e32 v82, v82
	v_cvt_pk_bf16_f32 v84, v86, v87
	v_mad_i64_i32 v[86:87], s[2:3], v98, s10, v[114:115]
	v_add_f32_e32 v82, 1.0, v82
	v_rcp_f32_e32 v82, v82
	v_lshl_add_u64 v[86:87], v[86:87], 0, v[116:117]
	v_mul_f32_e32 v82, v85, v82
	v_mul_f32_e32 v85, v82, v89
	v_cvt_pk_bf16_f32 v82, v90, v91
	v_cvt_pk_bf16_f32 v85, v88, v85
	global_store_dwordx4 v[86:87], v[82:85], off
	s_nop 1
	v_mul_f32_e32 v83, 0xbfb8aa3b, v74
	v_exp_f32_e32 v83, v83
	v_or_b32_e32 v82, 48, v0
	v_add_f32_e32 v83, 1.0, v83
	v_rcp_f32_e32 v83, v83
	s_nop 0
	v_mul_f32_e32 v74, v74, v83
	v_mul_f32_e32 v74, v74, v78
	v_mul_f32_e32 v78, 0xbfb8aa3b, v75
	v_exp_f32_e32 v78, v78
	s_nop 0
	v_add_f32_e32 v78, 1.0, v78
	v_rcp_f32_e32 v78, v78
	s_nop 0
	v_mul_f32_e32 v75, v75, v78
	v_mul_f32_e32 v78, 0xbfb8aa3b, v76
	v_exp_f32_e32 v78, v78
	v_mul_f32_e32 v75, v75, v79
	v_add_f32_e32 v78, 1.0, v78
	v_rcp_f32_e32 v78, v78
	s_nop 0
	v_mul_f32_e32 v76, v76, v78
	v_mul_f32_e32 v78, 0xbfb8aa3b, v77
	v_exp_f32_e32 v78, v78
	v_mul_f32_e32 v76, v76, v80
	v_add_f32_e32 v78, 1.0, v78
	v_rcp_f32_e32 v78, v78
	s_nop 0
	v_mul_f32_e32 v77, v77, v78
	v_mul_f32_e32 v78, 0xbfb8aa3b, v66
	v_exp_f32_e32 v78, v78
	v_mul_f32_e32 v77, v77, v81
	v_add_f32_e32 v78, 1.0, v78
	v_rcp_f32_e32 v78, v78
	s_nop 0
	v_mul_f32_e32 v66, v66, v78
	v_mul_f32_e32 v70, v66, v70
	v_mul_f32_e32 v66, 0xbfb8aa3b, v67
	v_exp_f32_e32 v66, v66
	s_nop 0
	v_add_f32_e32 v66, 1.0, v66
	v_rcp_f32_e32 v66, v66
	s_nop 0
	v_mul_f32_e32 v66, v67, v66
	v_mul_f32_e32 v71, v66, v71
	v_mul_f32_e32 v66, 0xbfb8aa3b, v68
	v_exp_f32_e32 v66, v66
	v_cvt_pk_bf16_f32 v67, v76, v77
	s_nop 0
	v_add_f32_e32 v66, 1.0, v66
	v_rcp_f32_e32 v66, v66
	s_nop 0
	v_mul_f32_e32 v66, v68, v66
	v_mul_f32_e32 v72, v66, v72
	v_mul_f32_e32 v66, 0xbfb8aa3b, v69
	v_exp_f32_e32 v66, v66
	v_cvt_pk_bf16_f32 v68, v70, v71
	v_mad_i64_i32 v[70:71], s[2:3], v82, s10, v[114:115]
	v_add_f32_e32 v66, 1.0, v66
	v_rcp_f32_e32 v66, v66
	v_lshl_add_u64 v[70:71], v[70:71], 0, v[116:117]
	v_mul_f32_e32 v66, v69, v66
	v_mul_f32_e32 v69, v66, v73
	v_cvt_pk_bf16_f32 v66, v74, v75
	v_cvt_pk_bf16_f32 v69, v72, v69
	global_store_dwordx4 v[70:71], v[66:69], off
	s_nop 1
	v_mul_f32_e32 v67, 0xbfb8aa3b, v58
	v_exp_f32_e32 v67, v67
	v_add_u32_e32 v66, 0x80, v0
	v_add_f32_e32 v67, 1.0, v67
	v_rcp_f32_e32 v67, v67
	s_nop 0
	v_mul_f32_e32 v58, v58, v67
	v_mul_f32_e32 v58, v58, v62
	v_mul_f32_e32 v62, 0xbfb8aa3b, v59
	v_exp_f32_e32 v62, v62
	s_nop 0
	v_add_f32_e32 v62, 1.0, v62
	v_rcp_f32_e32 v62, v62
	s_nop 0
	v_mul_f32_e32 v59, v59, v62
	v_mul_f32_e32 v62, 0xbfb8aa3b, v60
	v_exp_f32_e32 v62, v62
	v_mul_f32_e32 v59, v59, v63
	v_add_f32_e32 v62, 1.0, v62
	v_rcp_f32_e32 v62, v62
	s_nop 0
	v_mul_f32_e32 v60, v60, v62
	v_mul_f32_e32 v62, 0xbfb8aa3b, v61
	v_exp_f32_e32 v62, v62
	v_mul_f32_e32 v60, v60, v64
	v_add_f32_e32 v62, 1.0, v62
	v_rcp_f32_e32 v62, v62
	s_nop 0
	v_mul_f32_e32 v61, v61, v62
	v_mul_f32_e32 v62, 0xbfb8aa3b, v50
	v_exp_f32_e32 v62, v62
	v_mul_f32_e32 v61, v61, v65
	v_add_f32_e32 v62, 1.0, v62
	v_rcp_f32_e32 v62, v62
	s_nop 0
	v_mul_f32_e32 v50, v50, v62
	v_mul_f32_e32 v54, v50, v54
	v_mul_f32_e32 v50, 0xbfb8aa3b, v51
	v_exp_f32_e32 v50, v50
	s_nop 0
	v_add_f32_e32 v50, 1.0, v50
	v_rcp_f32_e32 v50, v50
	s_nop 0
	v_mul_f32_e32 v50, v51, v50
	v_mul_f32_e32 v55, v50, v55
	v_mul_f32_e32 v50, 0xbfb8aa3b, v52
	v_exp_f32_e32 v50, v50
	v_cvt_pk_bf16_f32 v51, v60, v61
	s_nop 0
	v_add_f32_e32 v50, 1.0, v50
	v_rcp_f32_e32 v50, v50
	s_nop 0
	v_mul_f32_e32 v50, v52, v50
	v_mul_f32_e32 v56, v50, v56
	v_mul_f32_e32 v50, 0xbfb8aa3b, v53
	v_exp_f32_e32 v50, v50
	v_cvt_pk_bf16_f32 v52, v54, v55
	v_mad_i64_i32 v[54:55], s[2:3], v66, s10, v[114:115]
	v_add_f32_e32 v50, 1.0, v50
	v_rcp_f32_e32 v50, v50
	v_lshl_add_u64 v[54:55], v[54:55], 0, v[116:117]
	v_mul_f32_e32 v50, v53, v50
	v_mul_f32_e32 v53, v50, v57
	v_cvt_pk_bf16_f32 v50, v58, v59
	v_cvt_pk_bf16_f32 v53, v56, v53
	global_store_dwordx4 v[54:55], v[50:53], off
	s_nop 1
	v_mul_f32_e32 v51, 0xbfb8aa3b, v42
	v_exp_f32_e32 v51, v51
	v_add_u32_e32 v50, 0x90, v0
	v_add_f32_e32 v51, 1.0, v51
	v_rcp_f32_e32 v51, v51
	s_nop 0
	v_mul_f32_e32 v42, v42, v51
	v_mul_f32_e32 v42, v42, v46
	v_mul_f32_e32 v46, 0xbfb8aa3b, v43
	v_exp_f32_e32 v46, v46
	s_nop 0
	v_add_f32_e32 v46, 1.0, v46
	v_rcp_f32_e32 v46, v46
	s_nop 0
	v_mul_f32_e32 v43, v43, v46
	v_mul_f32_e32 v46, 0xbfb8aa3b, v44
	v_exp_f32_e32 v46, v46
	v_mul_f32_e32 v43, v43, v47
	v_add_f32_e32 v46, 1.0, v46
	v_rcp_f32_e32 v46, v46
	s_nop 0
	v_mul_f32_e32 v44, v44, v46
	v_mul_f32_e32 v46, 0xbfb8aa3b, v45
	v_exp_f32_e32 v46, v46
	v_mul_f32_e32 v44, v44, v48
	v_add_f32_e32 v46, 1.0, v46
	v_rcp_f32_e32 v46, v46
	s_nop 0
	v_mul_f32_e32 v45, v45, v46
	v_mul_f32_e32 v46, 0xbfb8aa3b, v34
	v_exp_f32_e32 v46, v46
	v_mul_f32_e32 v45, v45, v49
	v_add_f32_e32 v46, 1.0, v46
	v_rcp_f32_e32 v46, v46
	s_nop 0
	v_mul_f32_e32 v34, v34, v46
	v_mul_f32_e32 v38, v34, v38
	v_mul_f32_e32 v34, 0xbfb8aa3b, v35
	v_exp_f32_e32 v34, v34
	s_nop 0
	v_add_f32_e32 v34, 1.0, v34
	v_rcp_f32_e32 v34, v34
	s_nop 0
	v_mul_f32_e32 v34, v35, v34
	v_mul_f32_e32 v39, v34, v39
	v_mul_f32_e32 v34, 0xbfb8aa3b, v36
	v_exp_f32_e32 v34, v34
	v_cvt_pk_bf16_f32 v35, v44, v45
	s_nop 0
	v_add_f32_e32 v34, 1.0, v34
	v_rcp_f32_e32 v34, v34
	s_nop 0
	v_mul_f32_e32 v34, v36, v34
	v_mul_f32_e32 v40, v34, v40
	v_mul_f32_e32 v34, 0xbfb8aa3b, v37
	v_exp_f32_e32 v34, v34
	v_cvt_pk_bf16_f32 v36, v38, v39
	v_mad_i64_i32 v[38:39], s[2:3], v50, s10, v[114:115]
	v_add_f32_e32 v34, 1.0, v34
	v_rcp_f32_e32 v34, v34
	v_lshl_add_u64 v[38:39], v[38:39], 0, v[116:117]
	v_mul_f32_e32 v34, v37, v34
	v_mul_f32_e32 v37, v34, v41
	v_cvt_pk_bf16_f32 v34, v42, v43
	v_cvt_pk_bf16_f32 v37, v40, v37
	global_store_dwordx4 v[38:39], v[34:37], off
	s_nop 1
	v_mul_f32_e32 v35, 0xbfb8aa3b, v26
	v_exp_f32_e32 v35, v35
	v_add_u32_e32 v34, 0xa0, v0
	v_add_u32_e32 v0, 0xb0, v0
	v_add_f32_e32 v35, 1.0, v35
	v_rcp_f32_e32 v35, v35
	s_nop 0
	v_mul_f32_e32 v26, v26, v35
	v_mul_f32_e32 v26, v26, v30
	v_mul_f32_e32 v30, 0xbfb8aa3b, v27
	v_exp_f32_e32 v30, v30
	s_nop 0
	v_add_f32_e32 v30, 1.0, v30
	v_rcp_f32_e32 v30, v30
	s_nop 0
	v_mul_f32_e32 v27, v27, v30
	v_mul_f32_e32 v30, 0xbfb8aa3b, v28
	v_exp_f32_e32 v30, v30
	v_mul_f32_e32 v27, v27, v31
	v_add_f32_e32 v30, 1.0, v30
	v_rcp_f32_e32 v30, v30
	s_nop 0
	v_mul_f32_e32 v28, v28, v30
	v_mul_f32_e32 v30, 0xbfb8aa3b, v29
	v_exp_f32_e32 v30, v30
	v_mul_f32_e32 v28, v28, v32
	v_add_f32_e32 v30, 1.0, v30
	v_rcp_f32_e32 v30, v30
	s_nop 0
	v_mul_f32_e32 v29, v29, v30
	v_mul_f32_e32 v30, 0xbfb8aa3b, v18
	v_exp_f32_e32 v30, v30
	v_mul_f32_e32 v29, v29, v33
	v_add_f32_e32 v30, 1.0, v30
	v_rcp_f32_e32 v30, v30
	s_nop 0
	v_mul_f32_e32 v18, v18, v30
	v_mul_f32_e32 v22, v18, v22
	v_mul_f32_e32 v18, 0xbfb8aa3b, v19
	v_exp_f32_e32 v18, v18
	s_nop 0
	v_add_f32_e32 v18, 1.0, v18
	v_rcp_f32_e32 v18, v18
	s_nop 0
	v_mul_f32_e32 v18, v19, v18
	v_mul_f32_e32 v23, v18, v23
	v_mul_f32_e32 v18, 0xbfb8aa3b, v20
	v_exp_f32_e32 v18, v18
	v_cvt_pk_bf16_f32 v19, v28, v29
	s_nop 0
	v_add_f32_e32 v18, 1.0, v18
	v_rcp_f32_e32 v18, v18
	s_nop 0
	v_mul_f32_e32 v18, v20, v18
	v_mul_f32_e32 v24, v18, v24
	v_mul_f32_e32 v18, 0xbfb8aa3b, v21
	v_exp_f32_e32 v18, v18
	v_cvt_pk_bf16_f32 v20, v22, v23
	v_mad_i64_i32 v[22:23], s[2:3], v34, s10, v[114:115]
	v_add_f32_e32 v18, 1.0, v18
	v_rcp_f32_e32 v18, v18
	v_lshl_add_u64 v[22:23], v[22:23], 0, v[116:117]
	v_mul_f32_e32 v18, v21, v18
	v_mul_f32_e32 v21, v18, v25
	v_cvt_pk_bf16_f32 v18, v26, v27
	v_cvt_pk_bf16_f32 v21, v24, v21
	global_store_dwordx4 v[22:23], v[18:21], off
	s_nop 1
	v_mul_f32_e32 v18, 0xbfb8aa3b, v10
	v_exp_f32_e32 v18, v18
	s_nop 0
	v_add_f32_e32 v18, 1.0, v18
	v_rcp_f32_e32 v18, v18
	s_nop 0
	v_mul_f32_e32 v10, v10, v18
	v_mul_f32_e32 v10, v10, v14
	v_mul_f32_e32 v14, 0xbfb8aa3b, v11
	v_exp_f32_e32 v14, v14
	s_nop 0
	v_add_f32_e32 v14, 1.0, v14
	v_rcp_f32_e32 v14, v14
	s_nop 0
	v_mul_f32_e32 v11, v11, v14
	v_mul_f32_e32 v14, 0xbfb8aa3b, v12
	v_exp_f32_e32 v14, v14
	v_mul_f32_e32 v11, v11, v15
	v_add_f32_e32 v14, 1.0, v14
	v_rcp_f32_e32 v14, v14
	s_nop 0
	v_mul_f32_e32 v12, v12, v14
	v_mul_f32_e32 v14, 0xbfb8aa3b, v13
	v_exp_f32_e32 v14, v14
	v_mul_f32_e32 v12, v12, v16
	v_add_f32_e32 v14, 1.0, v14
	v_rcp_f32_e32 v14, v14
	s_nop 0
	v_mul_f32_e32 v13, v13, v14
	v_mul_f32_e32 v14, 0xbfb8aa3b, v2
	v_exp_f32_e32 v14, v14
	v_mul_f32_e32 v13, v13, v17
	v_add_f32_e32 v14, 1.0, v14
	v_rcp_f32_e32 v14, v14
	s_nop 0
	v_mul_f32_e32 v2, v2, v14
	v_mul_f32_e32 v6, v2, v6
	v_mul_f32_e32 v2, 0xbfb8aa3b, v3
	v_exp_f32_e32 v2, v2
	s_nop 0
	v_add_f32_e32 v2, 1.0, v2
	v_rcp_f32_e32 v2, v2
	s_nop 0
	v_mul_f32_e32 v2, v3, v2
	v_mul_f32_e32 v7, v2, v7
	v_mul_f32_e32 v2, 0xbfb8aa3b, v4
	v_exp_f32_e32 v2, v2
	v_cvt_pk_bf16_f32 v3, v12, v13
	s_nop 0
	v_add_f32_e32 v2, 1.0, v2
	v_rcp_f32_e32 v2, v2
	s_nop 0
	v_mul_f32_e32 v2, v4, v2
	v_mul_f32_e32 v8, v2, v8
	v_mul_f32_e32 v2, 0xbfb8aa3b, v5
	v_exp_f32_e32 v2, v2
	v_cvt_pk_bf16_f32 v4, v6, v7
	v_mad_i64_i32 v[6:7], s[2:3], v0, s10, v[114:115]
	v_add_f32_e32 v2, 1.0, v2
	v_rcp_f32_e32 v2, v2
	v_lshl_add_u64 v[6:7], v[6:7], 0, v[116:117]
	v_mul_f32_e32 v2, v5, v2
	v_mul_f32_e32 v5, v2, v9
	v_cvt_pk_bf16_f32 v2, v10, v11
	v_cvt_pk_bf16_f32 v5, v8, v5
	global_store_dwordx4 v[6:7], v[2:5], off
	v_mbcnt_lo_u32_b32 v140, -1, 0
	v_mbcnt_hi_u32_b32 v140, -1, v140
	v_lshl_add_u32 v140, s69, 6, v140
	s_nop 0
	v_lshlrev_b32_e32 v141, 4, v140
	v_bfe_i32 v3, v140, 27, 1
	v_lshrrev_b32_e32 v3, 22, v3
	v_add_u32_e32 v3, v141, v3
	v_and_b32_e32 v3, 0xfffffc00, v3
	v_sub_u32_e32 v3, v141, v3
	v_lshrrev_b32_e32 v4, 4, v3
	v_bitop3_b32 v4, v4, v3, 32 bitop3:0x6c
	v_ashrrev_i32_e32 v3, 31, v3
	v_ashrrev_i32_e32 v0, 31, v140
	v_lshrrev_b32_e32 v3, 26, v3
	v_lshrrev_b32_e32 v0, 26, v0
	v_add_u32_e32 v3, v4, v3
	v_add_u32_e32 v0, v140, v0
	v_ashrrev_i32_e32 v3, 6, v3
	v_ashrrev_i32_e32 v0, 6, v0
	v_mul_i32_i24_e32 v6, 64, v3
	v_lshlrev_b32_e32 v5, 3, v0
	v_lshlrev_b32_e32 v0, 5, v0
	v_sub_u32_e32 v4, v4, v6
	v_add_u32_e32 v142, 0x2000, v141
	v_and_b32_e32 v0, 32, v0
	v_ashrrev_i16_sdwa v4, v217, sext(v4) dst_sel:DWORD dst_unused:UNUSED_PAD src0_sel:DWORD src1_sel:BYTE_0
	v_add_u32_sdwa v0, v0, sext(v4) dst_sel:DWORD dst_unused:UNUSED_PAD src0_sel:DWORD src1_sel:WORD_0
	v_ashrrev_i32_e32 v4, 31, v142
	v_lshrrev_b32_e32 v4, 22, v4
	v_add_u32_e32 v4, v142, v4
	v_ashrrev_i32_e32 v4, 10, v4
	v_mul_i32_i24_e32 v6, 0x400, v4
	v_sub_u32_e32 v6, v142, v6
	v_lshrrev_b32_e32 v7, 4, v6
	v_bitop3_b32 v6, v7, v6, 32 bitop3:0x6c
	v_ashrrev_i32_e32 v8, 31, v6
	v_lshrrev_b32_e32 v8, 26, v8
	v_add_u32_e32 v8, v6, v8
	v_lshrrev_b32_e32 v9, 6, v8
	v_and_b32_e32 v8, 0xc0, v8
	v_and_b32_e32 v5, 0x1ffff0, v5
	v_lshlrev_b32_e32 v7, 3, v4
	v_lshlrev_b32_e32 v4, 5, v4
	v_sub_u32_e32 v6, v6, v8
	v_and_b32_e32 v7, 0x1ffff0, v7
	v_and_b32_e32 v4, 32, v4
	v_ashrrev_i16_sdwa v6, v217, sext(v6) dst_sel:DWORD dst_unused:UNUSED_PAD src0_sel:DWORD src1_sel:BYTE_0
	v_add_lshl_u32 v3, v3, v5, 11
	v_add_u32_sdwa v4, v4, sext(v6) dst_sel:DWORD dst_unused:UNUSED_PAD src0_sel:DWORD src1_sel:WORD_0
	v_lshl_add_u32 v0, v0, 1, v3
	v_add_lshl_u32 v3, v9, v7, 11
	v_ashrrev_i32_e32 v2, 6, v140
	v_lshl_add_u32 v130, v4, 1, v3
	s_cbranch_vccnz .LBB0_928
	s_waitcnt vmcnt(8)
	s_branch .Lsw_head

.Lsw_head:
	v_ashrrev_i32_e32 v3, 8, v140
	v_cmp_eq_u32_e32 vcc, 1, v3
	s_and_saveexec_b64 s[2:3], vcc
	s_cbranch_execz .LBB0_922
	s_barrier
.LBB0_922:
	s_or_b64 exec, exec, s[2:3]
	s_ashr_i32 s25, s24, 31
	s_lshl_b64 s[10:11], s[24:25], 11
	s_add_u32 s2, s15, s10
	s_addc_u32 s3, s26, s11
	v_add_u32_e32 v149, s85, v141
	v_lshl_add_u64 v[4:5], s[2:3], 0, v[0:1]
	s_mov_b64 s[20:21], 0x80
	v_readfirstlane_b32 s16, v149
	v_lshl_add_u64 v[4:5], v[4:5], 0, s[20:21]
	s_mov_b32 m0, s16
	v_mov_b32_e32 v131, v1
	v_add_u32_e32 v150, s85, v142
	s_barrier
	global_load_lds_dwordx4 v[4:5], off
	v_lshl_add_u64 v[4:5], s[2:3], 0, v[130:131]
	v_readfirstlane_b32 s2, v150
	s_ashr_i32 s23, s22, 31
	v_add_u32_e32 v151, 16, v141
	s_mov_b32 m0, s2
	s_lshl_b64 s[2:3], s[22:23], 11
	v_add_u32_e32 v152, 0x8000, v151
	v_add_u32_e32 v153, 16, v142
	v_lshl_add_u64 v[4:5], v[4:5], 0, s[20:21]
	s_add_u32 s16, s28, s2
	v_readfirstlane_b32 s18, v152
	v_add_u32_e32 v154, 0x8000, v153
	global_load_lds_dwordx4 v[4:5], off
	s_addc_u32 s17, s29, s3
	s_mov_b32 m0, s18
	v_readfirstlane_b32 s18, v154
	global_load_lds_dwordx4 v0, s[16:17]
	s_mov_b32 m0, s18
	v_add_u32_e32 v156, s94, v141
	global_load_lds_dwordx4 v130, s[16:17]
	s_or_b32 s16, s24, 0x80
	s_ashr_i32 s17, s16, 31
	s_lshl_b64 s[16:17], s[16:17], 11
	s_add_u32 s16, s15, s16
	s_addc_u32 s17, s26, s17
	v_lshl_add_u64 v[4:5], s[16:17], 0, v[0:1]
	v_readfirstlane_b32 s18, v156
	v_lshl_add_u64 v[4:5], v[4:5], 0, s[20:21]
	s_mov_b32 m0, s18
	v_add_u32_e32 v157, s94, v142
	global_load_lds_dwordx4 v[4:5], off
	v_lshl_add_u64 v[4:5], s[16:17], 0, v[130:131]
	v_readfirstlane_b32 s16, v157
	v_lshl_add_u64 v[4:5], v[4:5], 0, s[20:21]
	s_mov_b32 m0, s16
	v_and_b32_e32 v7, 15, v140
	global_load_lds_dwordx4 v[4:5], off
	v_lshlrev_b32_e32 v2, 12, v2
	v_lshlrev_b32_e32 v5, 2, v140
	v_and_b32_e32 v6, 48, v140
	v_and_b32_e32 v4, 0x3000, v2
	v_lshlrev_b32_e32 v2, 6, v7
	v_and_b32_e32 v5, 32, v5
	v_lshlrev_b32_e32 v10, 6, v140
	s_movk_i32 s16, 0x3c0
	s_waitcnt vmcnt(14)
	v_bitop3_b32 v2, v2, v5, v6 bitop3:0x36
	v_lshlrev_b32_e32 v3, 13, v3
	v_and_or_b32 v6, v10, s16, v6
	s_add_u32 s10, s14, s10
	v_add_u32_e32 v7, s33, v2
	v_add_u32_e32 v8, 16, v2
	v_or_b32_e32 v9, 0x800, v3
	v_xad_u32 v5, v6, v5, 16
	v_or_b32_e32 v6, 0x1000, v3
	v_or_b32_e32 v10, 0x1800, v3
	v_add_u32_e32 v11, s86, v2
	v_add_u32_e32 v12, s85, v2
	v_add_u32_e32 v13, s94, v2
	s_addc_u32 s11, 0, s11
	v_mov_b32_e32 v2, 0
	s_mov_b32 s16, -2
	v_add_u32_e32 v158, v7, v4
	v_add_u32_e32 v146, v8, v3
	v_add_u32_e32 v145, v5, v9
	v_add_u32_e32 v144, v5, v6
	v_add_u32_e32 v143, v5, v10
	v_add_u32_e32 v155, v11, v4
	v_add_u32_e32 v148, v12, v4
	v_add_u32_e32 v147, v13, v4
	v_mov_b32_e32 v3, v2
	v_mov_b32_e32 v4, v2
	v_mov_b32_e32 v5, v2
	v_mov_b32_e32 v6, v2
	v_mov_b32_e32 v7, v2
	v_mov_b32_e32 v8, v2
	v_mov_b32_e32 v9, v2
	v_mov_b32_e32 v10, v2
	v_mov_b32_e32 v11, v2
	v_mov_b32_e32 v12, v2
	v_mov_b32_e32 v13, v2
	v_mov_b32_e32 v14, v2
	v_mov_b32_e32 v15, v2
	v_mov_b32_e32 v16, v2
	v_mov_b32_e32 v17, v2
	v_mov_b32_e32 v18, v2
	v_mov_b32_e32 v19, v2
	v_mov_b32_e32 v20, v2
	v_mov_b32_e32 v21, v2
	v_mov_b32_e32 v22, v2
	v_mov_b32_e32 v23, v2
	v_mov_b32_e32 v24, v2
	v_mov_b32_e32 v25, v2
	v_mov_b32_e32 v26, v2
	v_mov_b32_e32 v27, v2
	v_mov_b32_e32 v28, v2
	v_mov_b32_e32 v29, v2
	v_mov_b32_e32 v30, v2
	v_mov_b32_e32 v31, v2
	v_mov_b32_e32 v32, v2
	v_mov_b32_e32 v33, v2
	v_mov_b32_e32 v34, v2
	v_mov_b32_e32 v35, v2
	v_mov_b32_e32 v36, v2
	v_mov_b32_e32 v37, v2
	v_mov_b32_e32 v38, v2
	v_mov_b32_e32 v39, v2
	v_mov_b32_e32 v40, v2
	v_mov_b32_e32 v41, v2
	v_mov_b32_e32 v42, v2
	v_mov_b32_e32 v43, v2
	v_mov_b32_e32 v44, v2
	v_mov_b32_e32 v45, v2
	v_mov_b32_e32 v46, v2
	v_mov_b32_e32 v47, v2
	v_mov_b32_e32 v48, v2
	v_mov_b32_e32 v49, v2
	v_mov_b32_e32 v50, v2
	v_mov_b32_e32 v51, v2
	v_mov_b32_e32 v52, v2
	v_mov_b32_e32 v53, v2
	v_mov_b32_e32 v54, v2
	v_mov_b32_e32 v55, v2
	v_mov_b32_e32 v56, v2
	v_mov_b32_e32 v57, v2
	v_mov_b32_e32 v58, v2
	v_mov_b32_e32 v59, v2
	v_mov_b32_e32 v60, v2
	v_mov_b32_e32 v61, v2
	v_mov_b32_e32 v62, v2
	v_mov_b32_e32 v63, v2
	v_mov_b32_e32 v64, v2
	v_mov_b32_e32 v65, v2
	v_mov_b32_e32 v66, v2
	v_mov_b32_e32 v67, v2
	v_mov_b32_e32 v68, v2
	v_mov_b32_e32 v69, v2
	v_mov_b32_e32 v70, v2
	v_mov_b32_e32 v71, v2
	v_mov_b32_e32 v72, v2
	v_mov_b32_e32 v73, v2
	v_mov_b32_e32 v74, v2
	v_mov_b32_e32 v75, v2
	v_mov_b32_e32 v76, v2
	v_mov_b32_e32 v77, v2
	v_mov_b32_e32 v78, v2
	v_mov_b32_e32 v79, v2
	v_mov_b32_e32 v80, v2
	v_mov_b32_e32 v81, v2
	v_mov_b32_e32 v82, v2
	v_mov_b32_e32 v83, v2
	v_mov_b32_e32 v84, v2
	v_mov_b32_e32 v85, v2
	v_mov_b32_e32 v86, v2
	v_mov_b32_e32 v87, v2
	v_mov_b32_e32 v88, v2
	v_mov_b32_e32 v89, v2
	v_mov_b32_e32 v90, v2
	v_mov_b32_e32 v91, v2
	v_mov_b32_e32 v92, v2
	v_mov_b32_e32 v93, v2
	v_mov_b32_e32 v94, v2
	v_mov_b32_e32 v95, v2
	v_mov_b32_e32 v96, v2
	v_mov_b32_e32 v97, v2
	v_mov_b32_e32 v98, v2
	v_mov_b32_e32 v99, v2
	v_mov_b32_e32 v100, v2
	v_mov_b32_e32 v101, v2
	v_mov_b32_e32 v102, v2
	v_mov_b32_e32 v103, v2
	v_mov_b32_e32 v104, v2
	v_mov_b32_e32 v105, v2
	v_mov_b32_e32 v106, v2
	v_mov_b32_e32 v107, v2
	v_mov_b32_e32 v108, v2
	v_mov_b32_e32 v109, v2
	v_mov_b32_e32 v110, v2
	v_mov_b32_e32 v111, v2
	v_mov_b32_e32 v112, v2
	v_mov_b32_e32 v113, v2
	v_mov_b32_e32 v114, v2
	v_mov_b32_e32 v115, v2
	v_mov_b32_e32 v116, v2
	v_mov_b32_e32 v117, v2
	v_mov_b32_e32 v118, v2
	v_mov_b32_e32 v119, v2
	v_mov_b32_e32 v120, v2
	v_mov_b32_e32 v121, v2
	v_mov_b32_e32 v122, v2
	v_mov_b32_e32 v123, v2
	v_mov_b32_e32 v124, v2
	v_mov_b32_e32 v125, v2
	v_mov_b32_e32 v126, v2
	v_mov_b32_e32 v127, v2
	v_mov_b32_e32 v128, v2
	v_mov_b32_e32 v129, v2
	v_lshl_add_u64 v[132:133], s[2:3], 0, v[130:131]
	v_lshl_add_u64 v[134:135], s[2:3], 0, v[0:1]
	v_lshl_add_u64 v[136:137], s[10:11], 0, v[130:131]
	v_lshl_add_u64 v[138:139], s[10:11], 0, v[0:1]
	s_barrier
